# v57 + GEMM tile heads (z, wout, MLP1, MLP2): the 128 accumulators were zeroed twice per tile with 254 v_mov_b32; now once with 64 v_mov_b64
# speedup vs baseline: 1.0159x; 1.0104x over previous
; template <class Epi, class Sched>
; __device__ __forceinline__ void gemm_phase(LAS unsigned char* lds, const Gemm g, const Sched& S, const Epi& E) {
;     ...
;     f32x4 acc[2][2][4][2];
; #pragma unroll
;     for (int a = 0; a < 2; ++a)
; #pragma unroll
;         for (int b = 0; b < 2; ++b)
; #pragma unroll
;             for (int m = 0; m < 4; ++m)
; #pragma unroll
;                 for (int n = 0; n < 2; ++n) acc[a][b][m][n] = (f32x4){0.f, 0.f, 0.f, 0.f};
;     ...
; #pragma unroll
;         for (int a = 0; a < 2; ++a)
; #pragma unroll
;             for (int b = 0; b < 2; ++b)
; #pragma unroll
;                 for (int m = 0; m < 4; ++m)
; #pragma unroll
;                     for (int n = 0; n < 2; ++n) acc[a][b][m][n] = (f32x4){0.f, 0.f, 0.f, 0.f};
.LBB0_129:
	s_andn2_b64 vcc, exec, s[40:41]
	v_mov_b64_e32 v[2:3], 0
	v_mov_b64_e32 v[4:5], 0
	v_mov_b64_e32 v[6:7], 0
	v_mov_b64_e32 v[8:9], 0
	v_mov_b64_e32 v[10:11], 0
	v_mov_b64_e32 v[12:13], 0
	v_mov_b64_e32 v[14:15], 0
	v_mov_b64_e32 v[16:17], 0
	v_mov_b64_e32 v[18:19], 0
	v_mov_b64_e32 v[20:21], 0
	v_mov_b64_e32 v[22:23], 0
	v_mov_b64_e32 v[24:25], 0
	v_mov_b64_e32 v[26:27], 0
	v_mov_b64_e32 v[28:29], 0
	v_mov_b64_e32 v[30:31], 0
	v_mov_b64_e32 v[32:33], 0
	v_mov_b64_e32 v[34:35], 0
	v_mov_b64_e32 v[36:37], 0
	v_mov_b64_e32 v[38:39], 0
	v_mov_b64_e32 v[40:41], 0
	v_mov_b64_e32 v[42:43], 0
	v_mov_b64_e32 v[44:45], 0
	v_mov_b64_e32 v[46:47], 0
	v_mov_b64_e32 v[48:49], 0
	v_mov_b64_e32 v[50:51], 0
	v_mov_b64_e32 v[52:53], 0
	v_mov_b64_e32 v[54:55], 0
	v_mov_b64_e32 v[56:57], 0
	v_mov_b64_e32 v[58:59], 0
	v_mov_b64_e32 v[60:61], 0
	v_mov_b64_e32 v[62:63], 0
	v_mov_b64_e32 v[64:65], 0
	v_mov_b64_e32 v[66:67], 0
	v_mov_b64_e32 v[68:69], 0
	v_mov_b64_e32 v[70:71], 0
	v_mov_b64_e32 v[72:73], 0
	v_mov_b64_e32 v[74:75], 0
	v_mov_b64_e32 v[76:77], 0
	v_mov_b64_e32 v[78:79], 0
	v_mov_b64_e32 v[80:81], 0
	v_mov_b64_e32 v[82:83], 0
	v_mov_b64_e32 v[84:85], 0
	v_mov_b64_e32 v[86:87], 0
	v_mov_b64_e32 v[88:89], 0
	v_mov_b64_e32 v[90:91], 0
	v_mov_b64_e32 v[92:93], 0
	v_mov_b64_e32 v[94:95], 0
	v_mov_b64_e32 v[96:97], 0
	v_mov_b64_e32 v[98:99], 0
	v_mov_b64_e32 v[100:101], 0
	v_mov_b64_e32 v[102:103], 0
	v_mov_b64_e32 v[104:105], 0
	v_mov_b64_e32 v[106:107], 0
	v_mov_b64_e32 v[108:109], 0
	v_mov_b64_e32 v[110:111], 0
	v_mov_b64_e32 v[112:113], 0
	v_mov_b64_e32 v[114:115], 0
	v_mov_b64_e32 v[116:117], 0
	v_mov_b64_e32 v[118:119], 0
	v_mov_b64_e32 v[120:121], 0
	v_mov_b64_e32 v[122:123], 0
	v_mov_b64_e32 v[124:125], 0
	v_mov_b64_e32 v[126:127], 0
	v_mov_b64_e32 v[128:129], 0
	s_cbranch_vccnz .LBB0_132
	s_add_u32 s9, s46, 0x100
	s_addc_u32 s36, s47, 0
	s_mov_b32 s50, 0
	s_mov_b64 s[46:47], 0

; template <class Epi, class Sched>
; __device__ __forceinline__ void gemm_phase(LAS unsigned char* lds, const Gemm g, const Sched& S, const Epi& E) {
;     ...
;     f32x4 acc[2][2][4][2];
; #pragma unroll
;     for (int a = 0; a < 2; ++a)
; #pragma unroll
;         for (int b = 0; b < 2; ++b)
; #pragma unroll
;             for (int m = 0; m < 4; ++m)
; #pragma unroll
;                 for (int n = 0; n < 2; ++n) acc[a][b][m][n] = (f32x4){0.f, 0.f, 0.f, 0.f};
;     ...
; #pragma unroll
;         for (int a = 0; a < 2; ++a)
; #pragma unroll
;             for (int b = 0; b < 2; ++b)
; #pragma unroll
;                 for (int m = 0; m < 4; ++m)
; #pragma unroll
;                     for (int n = 0; n < 2; ++n) acc[a][b][m][n] = (f32x4){0.f, 0.f, 0.f, 0.f};
.LBB0_416:
	s_andn2_b64 vcc, exec, s[42:43]
	v_mov_b64_e32 v[2:3], 0
	v_mov_b64_e32 v[4:5], 0
	v_mov_b64_e32 v[6:7], 0
	v_mov_b64_e32 v[8:9], 0
	v_mov_b64_e32 v[10:11], 0
	v_mov_b64_e32 v[12:13], 0
	v_mov_b64_e32 v[14:15], 0
	v_mov_b64_e32 v[16:17], 0
	v_mov_b64_e32 v[18:19], 0
	v_mov_b64_e32 v[20:21], 0
	v_mov_b64_e32 v[22:23], 0
	v_mov_b64_e32 v[24:25], 0
	v_mov_b64_e32 v[26:27], 0
	v_mov_b64_e32 v[28:29], 0
	v_mov_b64_e32 v[30:31], 0
	v_mov_b64_e32 v[32:33], 0
	v_mov_b64_e32 v[34:35], 0
	v_mov_b64_e32 v[36:37], 0
	v_mov_b64_e32 v[38:39], 0
	v_mov_b64_e32 v[40:41], 0
	v_mov_b64_e32 v[42:43], 0
	v_mov_b64_e32 v[44:45], 0
	v_mov_b64_e32 v[46:47], 0
	v_mov_b64_e32 v[48:49], 0
	v_mov_b64_e32 v[50:51], 0
	v_mov_b64_e32 v[52:53], 0
	v_mov_b64_e32 v[54:55], 0
	v_mov_b64_e32 v[56:57], 0
	v_mov_b64_e32 v[58:59], 0
	v_mov_b64_e32 v[60:61], 0
	v_mov_b64_e32 v[62:63], 0
	v_mov_b64_e32 v[64:65], 0
	v_mov_b64_e32 v[66:67], 0
	v_mov_b64_e32 v[68:69], 0
	v_mov_b64_e32 v[70:71], 0
	v_mov_b64_e32 v[72:73], 0
	v_mov_b64_e32 v[74:75], 0
	v_mov_b64_e32 v[76:77], 0
	v_mov_b64_e32 v[78:79], 0
	v_mov_b64_e32 v[80:81], 0
	v_mov_b64_e32 v[82:83], 0
	v_mov_b64_e32 v[84:85], 0
	v_mov_b64_e32 v[86:87], 0
	v_mov_b64_e32 v[88:89], 0
	v_mov_b64_e32 v[90:91], 0
	v_mov_b64_e32 v[92:93], 0
	v_mov_b64_e32 v[94:95], 0
	v_mov_b64_e32 v[96:97], 0
	v_mov_b64_e32 v[98:99], 0
	v_mov_b64_e32 v[100:101], 0
	v_mov_b64_e32 v[102:103], 0
	v_mov_b64_e32 v[104:105], 0
	v_mov_b64_e32 v[106:107], 0
	v_mov_b64_e32 v[108:109], 0
	v_mov_b64_e32 v[110:111], 0
	v_mov_b64_e32 v[112:113], 0
	v_mov_b64_e32 v[114:115], 0
	v_mov_b64_e32 v[116:117], 0
	v_mov_b64_e32 v[118:119], 0
	v_mov_b64_e32 v[120:121], 0
	v_mov_b64_e32 v[122:123], 0
	v_mov_b64_e32 v[124:125], 0
	v_mov_b64_e32 v[126:127], 0
	v_mov_b64_e32 v[128:129], 0
	s_cbranch_vccnz .LBB0_419
	s_add_u32 s9, s48, 0x100
	s_addc_u32 s36, s49, 0
	s_mov_b32 s52, 0
	s_mov_b64 s[48:49], 0
